# MLA: s_setprio 1 for a wave while it is in its matrix block (PV + next QK), 0 in its vector block
# baseline (speedup 1.0000x reference)
; DI void mla_attn_phase(LAS unsigned char* lds, const bf16_t* Qg, const bf16_t* Kg, const bf16_t* Vtg, bf16_t* MIX) {
;     ...
;                 if (kt + 2 < NT) asm volatile("s_waitcnt vmcnt(4) lgkmcnt(0)" ::: "memory"); else asm volatile("s_waitcnt vmcnt(0) lgkmcnt(0)" ::: "memory");
;                 __builtin_amdgcn_s_barrier(); asm volatile("" ::: "memory");
.Lmla_z:
	s_setprio 0
	s_cmp_lt_u32 s34, 0x80
	s_cbranch_scc1 .Lmla_zb
	s_add_i32 s30, s42, 2
	s_cmp_ge_i32 s30, s38
	s_cbranch_scc1 .Lmla_zw0
	s_waitcnt vmcnt(4)
	s_branch .Lmla_zb

; DI void mla_attn_phase(LAS unsigned char* lds, const bf16_t* Qg, const bf16_t* Kg, const bf16_t* Vtg, bf16_t* MIX) {
;     ...
;                 __builtin_amdgcn_s_barrier(); asm volatile("" ::: "memory");
.Lmla_xb:
	s_barrier
	s_setprio 1
	s_cmp_gt_i32 s40, s39
	s_cbranch_scc1 .LBB0_367
	s_waitcnt lgkmcnt(6)
	v_mfma_f32_32x32x16_bf16 v[64:79], v[144:147], v[80:83], v[64:79]
	v_mfma_f32_32x32x16_bf16 v[48:63], v[140:143], v[80:83], v[48:63]
	s_waitcnt lgkmcnt(0)
	v_mfma_f32_32x32x16_bf16 v[32:47], v[148:151], v[80:83], v[32:47]
	v_mfma_f32_32x32x16_bf16 v[16:31], v[152:155], v[80:83], v[16:31]
	ds_read_b128 v[80:83], v1 offset:13376
	ds_read_b128 v[96:99], v1 offset:17984
	ds_read_b128 v[100:103], v1 offset:22592
	ds_read_b128 v[104:107], v1 offset:27200
	v_mfma_f32_32x32x16_bf16 v[64:79], v[136:139], v[88:91], v[64:79]
	v_mfma_f32_32x32x16_bf16 v[48:63], v[12:15], v[88:91], v[48:63]
	v_mfma_f32_32x32x16_bf16 v[32:47], v[4:7], v[88:91], v[32:47]
	v_mfma_f32_32x32x16_bf16 v[16:31], v[8:11], v[88:91], v[16:31]
	ds_read_b128 v[4:7], v1 offset:13408
	ds_read_b128 v[8:11], v1 offset:18016
	ds_read_b128 v[12:15], v1 offset:22624
	ds_read_b128 v[88:91], v1 offset:27232
	s_waitcnt lgkmcnt(4)
	v_mfma_f32_32x32x16_bf16 v[64:79], v[80:83], v[84:87], v[64:79]
	v_mov_b32_e32 v233, v236
	v_mfma_f32_32x32x16_bf16 v[48:63], v[96:99], v[84:87], v[48:63]
	v_mfma_f32_32x32x16_bf16 v[32:47], v[100:103], v[84:87], v[32:47]
	v_mfma_f32_32x32x16_bf16 v[16:31], v[104:107], v[84:87], v[16:31]
	s_waitcnt lgkmcnt(0)
	v_mfma_f32_32x32x16_bf16 v[64:79], v[4:7], v[92:95], v[64:79]
	v_mfma_f32_32x32x16_bf16 v[48:63], v[8:11], v[92:95], v[48:63]
	v_mfma_f32_32x32x16_bf16 v[32:47], v[12:15], v[92:95], v[32:47]
	v_mfma_f32_32x32x16_bf16 v[16:31], v[88:91], v[92:95], v[16:31]
	s_branch .LBB0_371
